# phase-1 GEMM streams across tiles: next tile's first loads issued in the last two K steps, no pipeline drain between tiles
# speedup vs baseline: 1.0058x; 1.0058x over previous
.LBB0_152:
	s_or_b64 exec, exec, s[0:1]
	s_and_b32 s0, s95, 7
	s_cmp_lg_u32 s0, 0
	s_cselect_b64 s[2:3], -1, 0
	s_lshr_b32 s8, s60, 3
	s_cmp_eq_u32 s0, 0
	s_cselect_b64 s[4:5], -1, 0
	s_and_b64 s[6:7], s[4:5], exec
	s_movk_i32 s0, 0x2c0
	s_cselect_b32 s30, s8, s60
	s_cselect_b32 s31, s0, 0x1600
	v_mov_b32_e32 v0, v208
	s_mov_b32 s1, 0
	s_cmp_ge_i32 s30, s31
	s_movk_i32 s33, 0x1600
	s_barrier
	s_cbranch_scc1 .LBB0_164
	s_mov_b32 s32, 0
	s_lshl_b32 s6, s60, 6
	s_and_b32 s34, s6, 0x1c0
	s_lshr_b32 s0, s95, 3
	s_add_i32 s35, s34, 0xfffffd80
	s_and_b64 s[4:5], s[4:5], exec
	s_cselect_b32 s36, s0, s95
	s_add_u32 s37, s92, 0x34000000
	s_addc_u32 s38, s93, 0
	s_add_u32 s39, s92, 0x36b00000
	s_addc_u32 s40, s93, 0
	s_add_u32 s4, s92, 0x8000000
	s_addc_u32 s5, s93, 0
	s_add_u32 s6, s92, 0x8016000
	s_addc_u32 s7, s93, 0
	s_add_u32 s8, s92, 0x802c000
	s_addc_u32 s9, s93, 0
	s_add_u32 s10, s92, 0x8042000
	s_addc_u32 s11, s93, 0
	s_add_u32 s12, s92, 0x8058000
	s_addc_u32 s13, s93, 0
	s_add_u32 s14, s92, 0x806e000
	s_addc_u32 s15, s93, 0
	s_add_u32 s16, s92, 0x8084000
	s_addc_u32 s17, s93, 0
	s_add_u32 s18, s92, 0x809a000
	s_addc_u32 s19, s93, 0
	v_mov_b32_e32 v181, 0
	s_mov_b32 s41, 0x10000
	s_mov_b32 s42, 0x20000
	s_mov_b32 s43, 0x30000
	s_mov_b32 s44, 0x8000
	s_mov_b32 s45, 0x18000
	s_brev_b32 s46, 44
	s_mov_b32 s47, 0x34008000
	s_mov_b32 s48, 0x34010000
	s_mov_b32 s49, 0x34018000
	s_movk_i32 s50, 0x1000
	s_mov_b32 s51, 0x9000
	s_mov_b32 s52, 0x11000
	s_mov_b32 s53, 0x19000
	s_mov_b64 s[20:21], 0x1000
	s_mov_b64 s[22:23], 0x100
	v_mov_b32_e32 v190, 0x1600

.LBB0_161:
	v_and_b32_e32 v246, 63, v208
	v_lshrrev_b32_e32 v247, 6, v208
	v_lshrrev_b32_e32 v248, 3, v246
	v_and_b32_e32 v249, 7, v246
	v_xor_b32_e32 v249, v249, v248
	v_lshlrev_b32_e32 v249, 4, v249
	v_lshl_add_u32 v250, v247, 5, v248
	v_lshl_add_u32 v234, v250, 11, v249
	v_add_u32_e32 v235, 0x4000, v234
	v_add_u32_e32 v236, 0x8000, v234
	v_add_u32_e32 v237, 0xc000, v234
	v_lshlrev_b32_e32 v238, 4, v246
	v_add_u32_e32 v239, 0x8000, v238
	v_add_u32_e32 v240, 0x10000, v238
	v_add_u32_e32 v241, 0x18000, v238
	v_readfirstlane_b32 s0, v247
	s_lshl_b32 s97, s0, 12
	v_and_b32_e32 v251, 15, v246
	v_lshrrev_b32_e32 v252, 4, v246
	v_and_b32_e32 v253, 7, v251
	v_xor_b32_e32 v253, v253, v252
	v_lshlrev_b32_e32 v253, 4, v253
	v_lshl_add_u32 v242, v251, 7, v253
	v_xor_b32_e32 v243, 64, v242
	v_lshlrev_b32_e32 v244, 2, v251
	s_lshl_b32 s0, s24, 9
	s_add_i32 s0, s0, 0x36b00000
	v_add_u32_e32 v244, s0, v244
	v_mov_b32_e32 v245, s93
	v_add_co_u32_e32 v244, vcc, s92, v244
	s_nop 1
	v_addc_co_u32_e32 v245, vcc, 0, v245, vcc
	global_load_dword v246, v[244:245], off
	global_load_dword v247, v[244:245], off offset:64
	global_load_dword v248, v[244:245], off offset:128
	global_load_dword v249, v[244:245], off offset:192
	global_load_dword v250, v[244:245], off offset:256
	global_load_dword v251, v[244:245], off offset:320
	global_load_dword v252, v[244:245], off offset:384
	global_load_dword v253, v[244:245], off offset:448
	v_mov_b32_e32 v0, 0
	v_mov_b32_e32 v1, 0
	v_mov_b32_e32 v2, 0
	v_mov_b32_e32 v3, 0
	v_mov_b32_e32 v4, 0
	v_mov_b32_e32 v5, 0
	v_mov_b32_e32 v6, 0
	v_mov_b32_e32 v7, 0
	v_mov_b32_e32 v8, 0
	v_mov_b32_e32 v9, 0
	v_mov_b32_e32 v10, 0
	v_mov_b32_e32 v11, 0
	v_mov_b32_e32 v12, 0
	v_mov_b32_e32 v13, 0
	v_mov_b32_e32 v14, 0
	v_mov_b32_e32 v15, 0
	v_mov_b32_e32 v16, 0
	v_mov_b32_e32 v17, 0
	v_mov_b32_e32 v18, 0
	v_mov_b32_e32 v19, 0
	v_mov_b32_e32 v20, 0
	v_mov_b32_e32 v21, 0
	v_mov_b32_e32 v22, 0
	v_mov_b32_e32 v23, 0
	v_mov_b32_e32 v24, 0
	v_mov_b32_e32 v25, 0
	v_mov_b32_e32 v26, 0
	v_mov_b32_e32 v27, 0
	v_mov_b32_e32 v28, 0
	v_mov_b32_e32 v29, 0
	v_mov_b32_e32 v30, 0
	v_mov_b32_e32 v31, 0
	v_mov_b32_e32 v32, 0
	v_mov_b32_e32 v33, 0
	v_mov_b32_e32 v34, 0
	v_mov_b32_e32 v35, 0
	v_mov_b32_e32 v36, 0
	v_mov_b32_e32 v37, 0
	v_mov_b32_e32 v38, 0
	v_mov_b32_e32 v39, 0
	v_mov_b32_e32 v40, 0
	v_mov_b32_e32 v41, 0
	v_mov_b32_e32 v42, 0
	v_mov_b32_e32 v43, 0
	v_mov_b32_e32 v44, 0
	v_mov_b32_e32 v45, 0
	v_mov_b32_e32 v46, 0
	v_mov_b32_e32 v47, 0
	v_mov_b32_e32 v48, 0
	v_mov_b32_e32 v49, 0
	v_mov_b32_e32 v50, 0
	v_mov_b32_e32 v51, 0
	v_mov_b32_e32 v52, 0
	v_mov_b32_e32 v53, 0
	v_mov_b32_e32 v54, 0
	v_mov_b32_e32 v55, 0
	v_mov_b32_e32 v56, 0
	v_mov_b32_e32 v57, 0
	v_mov_b32_e32 v58, 0
	v_mov_b32_e32 v59, 0
	v_mov_b32_e32 v60, 0
	v_mov_b32_e32 v61, 0
	v_mov_b32_e32 v62, 0
	v_mov_b32_e32 v63, 0
	v_mov_b32_e32 v64, 0
	v_mov_b32_e32 v65, 0
	v_mov_b32_e32 v66, 0
	v_mov_b32_e32 v67, 0
	v_mov_b32_e32 v68, 0
	v_mov_b32_e32 v69, 0
	v_mov_b32_e32 v70, 0
	v_mov_b32_e32 v71, 0
	v_mov_b32_e32 v72, 0
	v_mov_b32_e32 v73, 0
	v_mov_b32_e32 v74, 0
	v_mov_b32_e32 v75, 0
	v_mov_b32_e32 v76, 0
	v_mov_b32_e32 v77, 0
	v_mov_b32_e32 v78, 0
	v_mov_b32_e32 v79, 0
	v_mov_b32_e32 v80, 0
	v_mov_b32_e32 v81, 0
	v_mov_b32_e32 v82, 0
	v_mov_b32_e32 v83, 0
	v_mov_b32_e32 v84, 0
	v_mov_b32_e32 v85, 0
	v_mov_b32_e32 v86, 0
	v_mov_b32_e32 v87, 0
	v_mov_b32_e32 v88, 0
	v_mov_b32_e32 v89, 0
	v_mov_b32_e32 v90, 0
	v_mov_b32_e32 v91, 0
	v_mov_b32_e32 v92, 0
	v_mov_b32_e32 v93, 0
	v_mov_b32_e32 v94, 0
	v_mov_b32_e32 v95, 0
	v_mov_b32_e32 v96, 0
	v_mov_b32_e32 v97, 0
	v_mov_b32_e32 v98, 0
	v_mov_b32_e32 v99, 0
	v_mov_b32_e32 v100, 0
	v_mov_b32_e32 v101, 0
	v_mov_b32_e32 v102, 0
	v_mov_b32_e32 v103, 0
	v_mov_b32_e32 v104, 0
	v_mov_b32_e32 v105, 0
	v_mov_b32_e32 v106, 0
	v_mov_b32_e32 v107, 0
	v_mov_b32_e32 v108, 0
	v_mov_b32_e32 v109, 0
	v_mov_b32_e32 v110, 0
	v_mov_b32_e32 v111, 0
	v_mov_b32_e32 v112, 0
	v_mov_b32_e32 v113, 0
	v_mov_b32_e32 v114, 0
	v_mov_b32_e32 v115, 0
	v_mov_b32_e32 v116, 0
	v_mov_b32_e32 v117, 0
	v_mov_b32_e32 v118, 0
	v_mov_b32_e32 v119, 0
	v_mov_b32_e32 v120, 0
	v_mov_b32_e32 v121, 0
	v_mov_b32_e32 v122, 0
	v_mov_b32_e32 v123, 0
	v_mov_b32_e32 v124, 0
	v_mov_b32_e32 v125, 0
	v_mov_b32_e32 v126, 0
	v_mov_b32_e32 v127, 0
	s_lshr_b32 s0, s32, 16
	s_and_b32 s28, s32, 0xffff
	s_add_i32 s27, s28, 0x8000
	s_cmp_lt_u32 s27, 0xc000
	s_cselect_b32 s0, s0, s0
	s_cbranch_scc1 .Lg1_nowrap
	s_sub_i32 s27, s27, 0xc000
.Lg1_nowrap:
	s_cmp_eq_u32 s0, 0x600d
	s_cbranch_scc1 .Lg1_pre
	s_lshl_b32 s0, s24, 18
	s_add_u32 s58, s92, s0
	s_addc_u32 s59, s93, 0
	s_lshl_b32 s0, s97, 5
	s_lshl_b32 s25, s26, 19
	s_add_i32 s0, s0, s25
	s_add_u32 s56, s92, s0
	s_addc_u32 s57, s93, 0
	s_add_u32 s56, s56, 0x34000000
	s_addc_u32 s57, s57, 0
	s_mov_b32 s25, 0
	s_mov_b32 s27, 0
	s_add_i32 m0, s27, s97
	s_nop 0
	global_load_lds_dwordx4 v234, s[58:59]
	s_add_i32 m0, m0, 0x400
	s_nop 0
	global_load_lds_dwordx4 v235, s[58:59]
	s_add_i32 m0, m0, 0x400
	s_nop 0
	global_load_lds_dwordx4 v236, s[58:59]
	s_add_i32 m0, m0, 0x400
	s_nop 0
	global_load_lds_dwordx4 v237, s[58:59]
	s_add_u32 s58, s58, 128
	s_addc_u32 s59, s59, 0
	global_load_dwordx4 v[128:131], v238, s[56:57]
	global_load_dwordx4 v[132:135], v239, s[56:57]
	global_load_dwordx4 v[136:139], v240, s[56:57]
	global_load_dwordx4 v[140:143], v241, s[56:57]
	s_add_u32 s56, s56, 1024
	s_addc_u32 s57, s57, 0
	s_add_i32 s25, s25, 1
	global_load_dwordx4 v[144:147], v238, s[56:57]
	global_load_dwordx4 v[148:151], v239, s[56:57]
	global_load_dwordx4 v[152:155], v240, s[56:57]
	global_load_dwordx4 v[156:159], v241, s[56:57]
	s_add_u32 s56, s56, 1024
	s_addc_u32 s57, s57, 0
	s_add_i32 s25, s25, 1
	s_movk_i32 s27, 0x4000
	s_add_i32 m0, s27, s97
	s_nop 0
	global_load_lds_dwordx4 v234, s[58:59]
	s_add_i32 m0, m0, 0x400
	s_nop 0
	global_load_lds_dwordx4 v235, s[58:59]
	s_add_i32 m0, m0, 0x400
	s_nop 0
	global_load_lds_dwordx4 v236, s[58:59]
	s_add_i32 m0, m0, 0x400
	s_nop 0
	global_load_lds_dwordx4 v237, s[58:59]
	s_add_u32 s58, s58, 128
	s_addc_u32 s59, s59, 0
	global_load_dwordx4 v[160:163], v238, s[56:57]
	global_load_dwordx4 v[164:167], v239, s[56:57]
	global_load_dwordx4 v[168:171], v240, s[56:57]
	global_load_dwordx4 v[172:175], v241, s[56:57]
	s_add_u32 s56, s56, 1024
	s_addc_u32 s57, s57, 0
	s_add_i32 s25, s25, 1
	s_mov_b32 s28, 0
	s_mov_b32 s27, 0x8000
.Lg1_pre:
	s_mov_b32 s25, 3
	s_mov_b32 s29, 0
.Lg1_loop:
	s_waitcnt vmcnt(12)
	s_barrier
	global_load_dwordx4 v[176:179], v238, s[56:57]
	global_load_dwordx4 v[182:185], v239, s[56:57]
	global_load_dwordx4 v[186:189], v240, s[56:57]
	global_load_dwordx4 v[194:197], v241, s[56:57]
	s_cmp_eq_u32 s25, 31
	s_cbranch_scc1 .Lg1_sww0
	s_add_u32 s56, s56, 1024
	s_addc_u32 s57, s57, 0
	s_branch .Lg1_swdw0
.Lg1_sww0:
	s_add_i32 s0, s30, s36
	s_cmp_lt_i32 s0, s31
	s_cbranch_scc0 .Lg1_nnw0
	s_cmp_eq_u64 s[2:3], 0
	s_cbranch_scc0 .Lg1_nnw0
	s_cmpk_gt_i32 s0, 0x27f
	s_cbranch_scc1 .Lg1_tlw0
	s_ashr_i32 vcc_lo, s0, 6
	s_and_b32 vcc_lo, vcc_lo, -2
	s_and_b32 vcc_hi, s0, 1
	s_or_b32 vcc_lo, vcc_lo, vcc_hi
	s_branch .Lg1_hvw0
.Lg1_tlw0:
	s_mov_b32 vcc_lo, 10
.Lg1_hvw0:
	s_lshl_b32 vcc_lo, vcc_lo, 19
	s_lshl_b32 vcc_hi, s97, 5
	s_add_i32 vcc_lo, vcc_lo, vcc_hi
	s_add_u32 s56, s92, vcc_lo
	s_addc_u32 s57, s93, 0
	s_add_u32 s56, s56, 0x34000000
	s_addc_u32 s57, s57, 0
	s_branch .Lg1_ndw0
.Lg1_nnw0:
	s_add_u32 s56, s56, 0
.Lg1_ndw0:
.Lg1_swdw0:
	s_add_i32 s25, s25, 1
	s_add_i32 m0, s27, s97
	s_nop 0
	global_load_lds_dwordx4 v234, s[58:59]
	s_add_i32 m0, m0, 0x400
	s_nop 0
	global_load_lds_dwordx4 v235, s[58:59]
	s_add_i32 m0, m0, 0x400
	s_nop 0
	global_load_lds_dwordx4 v236, s[58:59]
	s_add_i32 m0, m0, 0x400
	s_nop 0
	global_load_lds_dwordx4 v237, s[58:59]
	s_cmp_eq_u32 s29, 13
	s_cbranch_scc1 .Lg1_saa1
	s_add_u32 s58, s58, 128
	s_addc_u32 s59, s59, 0
	s_branch .Lg1_sada1
.Lg1_saa1:
	s_add_i32 s0, s30, s36
	s_cmp_lt_i32 s0, s31
	s_cbranch_scc0 .Lg1_nna1
	s_cmp_eq_u64 s[2:3], 0
	s_cbranch_scc0 .Lg1_nna1
	s_cmpk_gt_i32 s0, 0x27f
	s_cbranch_scc1 .Lg1_tla1
	s_bfe_u32 vcc_lo, s0, 0x60001
	s_or_b32 vcc_lo, vcc_lo, s34
	s_branch .Lg1_hva1
.Lg1_tla1:
	s_add_i32 vcc_lo, s35, s0
.Lg1_hva1:
	s_lshl_b32 vcc_lo, vcc_lo, 18
	s_add_u32 s58, s92, vcc_lo
	s_addc_u32 s59, s93, 0
	s_branch .Lg1_nda1
.Lg1_nna1:
	s_add_u32 s58, s58, 0
.Lg1_nda1:
.Lg1_sada1:
	v_add_u32_e32 v244, s28, v242
	v_add_u32_e32 v245, s28, v243
	ds_read_b128 v[198:201], v244 offset:0
	ds_read_b128 v[202:205], v244 offset:2048
	ds_read_b128 v[210:213], v244 offset:4096
	ds_read_b128 v[214:217], v244 offset:6144
	ds_read_b128 v[218:221], v244 offset:8192
	ds_read_b128 v[222:225], v244 offset:10240
	ds_read_b128 v[226:229], v244 offset:12288
	ds_read_b128 v[230:233], v244 offset:14336
	s_waitcnt lgkmcnt(4)
	v_mfma_f32_16x16x32_bf16 v[0:3], v[128:131], v[198:201], v[0:3]
	v_mfma_f32_16x16x32_bf16 v[32:35], v[132:135], v[198:201], v[32:35]
	v_mfma_f32_16x16x32_bf16 v[64:67], v[136:139], v[198:201], v[64:67]
	v_mfma_f32_16x16x32_bf16 v[96:99], v[140:143], v[198:201], v[96:99]
	v_mfma_f32_16x16x32_bf16 v[4:7], v[128:131], v[202:205], v[4:7]
	v_mfma_f32_16x16x32_bf16 v[36:39], v[132:135], v[202:205], v[36:39]
	v_mfma_f32_16x16x32_bf16 v[68:71], v[136:139], v[202:205], v[68:71]
	v_mfma_f32_16x16x32_bf16 v[100:103], v[140:143], v[202:205], v[100:103]
	v_mfma_f32_16x16x32_bf16 v[8:11], v[128:131], v[210:213], v[8:11]
	v_mfma_f32_16x16x32_bf16 v[40:43], v[132:135], v[210:213], v[40:43]
	v_mfma_f32_16x16x32_bf16 v[72:75], v[136:139], v[210:213], v[72:75]
	v_mfma_f32_16x16x32_bf16 v[104:107], v[140:143], v[210:213], v[104:107]
	v_mfma_f32_16x16x32_bf16 v[12:15], v[128:131], v[214:217], v[12:15]
	v_mfma_f32_16x16x32_bf16 v[44:47], v[132:135], v[214:217], v[44:47]
	v_mfma_f32_16x16x32_bf16 v[76:79], v[136:139], v[214:217], v[76:79]
	v_mfma_f32_16x16x32_bf16 v[108:111], v[140:143], v[214:217], v[108:111]
	s_waitcnt lgkmcnt(0)
	v_mfma_f32_16x16x32_bf16 v[16:19], v[128:131], v[218:221], v[16:19]
	v_mfma_f32_16x16x32_bf16 v[48:51], v[132:135], v[218:221], v[48:51]
	v_mfma_f32_16x16x32_bf16 v[80:83], v[136:139], v[218:221], v[80:83]
	v_mfma_f32_16x16x32_bf16 v[112:115], v[140:143], v[218:221], v[112:115]
	v_mfma_f32_16x16x32_bf16 v[20:23], v[128:131], v[222:225], v[20:23]
	v_mfma_f32_16x16x32_bf16 v[52:55], v[132:135], v[222:225], v[52:55]
	v_mfma_f32_16x16x32_bf16 v[84:87], v[136:139], v[222:225], v[84:87]
	v_mfma_f32_16x16x32_bf16 v[116:119], v[140:143], v[222:225], v[116:119]
	v_mfma_f32_16x16x32_bf16 v[24:27], v[128:131], v[226:229], v[24:27]
	v_mfma_f32_16x16x32_bf16 v[56:59], v[132:135], v[226:229], v[56:59]
	v_mfma_f32_16x16x32_bf16 v[88:91], v[136:139], v[226:229], v[88:91]
	v_mfma_f32_16x16x32_bf16 v[120:123], v[140:143], v[226:229], v[120:123]
	v_mfma_f32_16x16x32_bf16 v[28:31], v[128:131], v[230:233], v[28:31]
	v_mfma_f32_16x16x32_bf16 v[60:63], v[132:135], v[230:233], v[60:63]
	v_mfma_f32_16x16x32_bf16 v[92:95], v[136:139], v[230:233], v[92:95]
	v_mfma_f32_16x16x32_bf16 v[124:127], v[140:143], v[230:233], v[124:127]
	s_waitcnt vmcnt(16)
	global_load_dwordx4 v[128:131], v238, s[56:57]
	global_load_dwordx4 v[132:135], v239, s[56:57]
	global_load_dwordx4 v[136:139], v240, s[56:57]
	global_load_dwordx4 v[140:143], v241, s[56:57]
	s_cmp_eq_u32 s25, 31
	s_cbranch_scc1 .Lg1_sww2
	s_add_u32 s56, s56, 1024
	s_addc_u32 s57, s57, 0
	s_branch .Lg1_swdw2

.Lg1_ndw2:
.Lg1_swdw2:
	s_add_i32 s25, s25, 1
	ds_read_b128 v[198:201], v245 offset:0
	ds_read_b128 v[202:205], v245 offset:2048
	ds_read_b128 v[210:213], v245 offset:4096
	ds_read_b128 v[214:217], v245 offset:6144
	ds_read_b128 v[218:221], v245 offset:8192
	ds_read_b128 v[222:225], v245 offset:10240
	ds_read_b128 v[226:229], v245 offset:12288
	ds_read_b128 v[230:233], v245 offset:14336
	s_waitcnt lgkmcnt(4)
	v_mfma_f32_16x16x32_bf16 v[0:3], v[144:147], v[198:201], v[0:3]
	v_mfma_f32_16x16x32_bf16 v[32:35], v[148:151], v[198:201], v[32:35]
	v_mfma_f32_16x16x32_bf16 v[64:67], v[152:155], v[198:201], v[64:67]
	v_mfma_f32_16x16x32_bf16 v[96:99], v[156:159], v[198:201], v[96:99]
	v_mfma_f32_16x16x32_bf16 v[4:7], v[144:147], v[202:205], v[4:7]
	v_mfma_f32_16x16x32_bf16 v[36:39], v[148:151], v[202:205], v[36:39]
	v_mfma_f32_16x16x32_bf16 v[68:71], v[152:155], v[202:205], v[68:71]
	v_mfma_f32_16x16x32_bf16 v[100:103], v[156:159], v[202:205], v[100:103]
	v_mfma_f32_16x16x32_bf16 v[8:11], v[144:147], v[210:213], v[8:11]
	v_mfma_f32_16x16x32_bf16 v[40:43], v[148:151], v[210:213], v[40:43]
	v_mfma_f32_16x16x32_bf16 v[72:75], v[152:155], v[210:213], v[72:75]
	v_mfma_f32_16x16x32_bf16 v[104:107], v[156:159], v[210:213], v[104:107]
	v_mfma_f32_16x16x32_bf16 v[12:15], v[144:147], v[214:217], v[12:15]
	v_mfma_f32_16x16x32_bf16 v[44:47], v[148:151], v[214:217], v[44:47]
	v_mfma_f32_16x16x32_bf16 v[76:79], v[152:155], v[214:217], v[76:79]
	v_mfma_f32_16x16x32_bf16 v[108:111], v[156:159], v[214:217], v[108:111]
	s_waitcnt lgkmcnt(0)
	v_mfma_f32_16x16x32_bf16 v[16:19], v[144:147], v[218:221], v[16:19]
	v_mfma_f32_16x16x32_bf16 v[48:51], v[148:151], v[218:221], v[48:51]
	v_mfma_f32_16x16x32_bf16 v[80:83], v[152:155], v[218:221], v[80:83]
	v_mfma_f32_16x16x32_bf16 v[112:115], v[156:159], v[218:221], v[112:115]
	v_mfma_f32_16x16x32_bf16 v[20:23], v[144:147], v[222:225], v[20:23]
	v_mfma_f32_16x16x32_bf16 v[52:55], v[148:151], v[222:225], v[52:55]
	v_mfma_f32_16x16x32_bf16 v[84:87], v[152:155], v[222:225], v[84:87]
	v_mfma_f32_16x16x32_bf16 v[116:119], v[156:159], v[222:225], v[116:119]
	v_mfma_f32_16x16x32_bf16 v[24:27], v[144:147], v[226:229], v[24:27]
	v_mfma_f32_16x16x32_bf16 v[56:59], v[148:151], v[226:229], v[56:59]
	v_mfma_f32_16x16x32_bf16 v[88:91], v[152:155], v[226:229], v[88:91]
	v_mfma_f32_16x16x32_bf16 v[120:123], v[156:159], v[226:229], v[120:123]
	v_mfma_f32_16x16x32_bf16 v[28:31], v[144:147], v[230:233], v[28:31]
	v_mfma_f32_16x16x32_bf16 v[60:63], v[148:151], v[230:233], v[60:63]
	v_mfma_f32_16x16x32_bf16 v[92:95], v[152:155], v[230:233], v[92:95]
	v_mfma_f32_16x16x32_bf16 v[124:127], v[156:159], v[230:233], v[124:127]
	s_add_i32 s28, s28, 0x4000
	s_cmp_lt_u32 s28, 0xc000
	s_cselect_b32 s28, s28, 0
	s_add_i32 s27, s27, 0x4000
	s_cmp_lt_u32 s27, 0xc000
	s_cselect_b32 s27, s27, 0
	s_add_i32 s29, s29, 1
	s_waitcnt vmcnt(12)
	s_barrier
	global_load_dwordx4 v[144:147], v238, s[56:57]
	global_load_dwordx4 v[148:151], v239, s[56:57]
	global_load_dwordx4 v[152:155], v240, s[56:57]
	global_load_dwordx4 v[156:159], v241, s[56:57]
	s_cmp_eq_u32 s25, 31
	s_cbranch_scc1 .Lg1_sww3
	s_add_u32 s56, s56, 1024
	s_addc_u32 s57, s57, 0
	s_branch .Lg1_swdw3

.Lg1_nda4:
.Lg1_sada4:
	v_add_u32_e32 v244, s28, v242
	v_add_u32_e32 v245, s28, v243
	ds_read_b128 v[198:201], v244 offset:0
	ds_read_b128 v[202:205], v244 offset:2048
	ds_read_b128 v[210:213], v244 offset:4096
	ds_read_b128 v[214:217], v244 offset:6144
	ds_read_b128 v[218:221], v244 offset:8192
	ds_read_b128 v[222:225], v244 offset:10240
	ds_read_b128 v[226:229], v244 offset:12288
	ds_read_b128 v[230:233], v244 offset:14336
	s_waitcnt lgkmcnt(4)
	v_mfma_f32_16x16x32_bf16 v[0:3], v[160:163], v[198:201], v[0:3]
	v_mfma_f32_16x16x32_bf16 v[32:35], v[164:167], v[198:201], v[32:35]
	v_mfma_f32_16x16x32_bf16 v[64:67], v[168:171], v[198:201], v[64:67]
	v_mfma_f32_16x16x32_bf16 v[96:99], v[172:175], v[198:201], v[96:99]
	v_mfma_f32_16x16x32_bf16 v[4:7], v[160:163], v[202:205], v[4:7]
	v_mfma_f32_16x16x32_bf16 v[36:39], v[164:167], v[202:205], v[36:39]
	v_mfma_f32_16x16x32_bf16 v[68:71], v[168:171], v[202:205], v[68:71]
	v_mfma_f32_16x16x32_bf16 v[100:103], v[172:175], v[202:205], v[100:103]
	v_mfma_f32_16x16x32_bf16 v[8:11], v[160:163], v[210:213], v[8:11]
	v_mfma_f32_16x16x32_bf16 v[40:43], v[164:167], v[210:213], v[40:43]
	v_mfma_f32_16x16x32_bf16 v[72:75], v[168:171], v[210:213], v[72:75]
	v_mfma_f32_16x16x32_bf16 v[104:107], v[172:175], v[210:213], v[104:107]
	v_mfma_f32_16x16x32_bf16 v[12:15], v[160:163], v[214:217], v[12:15]
	v_mfma_f32_16x16x32_bf16 v[44:47], v[164:167], v[214:217], v[44:47]
	v_mfma_f32_16x16x32_bf16 v[76:79], v[168:171], v[214:217], v[76:79]
	v_mfma_f32_16x16x32_bf16 v[108:111], v[172:175], v[214:217], v[108:111]
	s_waitcnt lgkmcnt(0)
	v_mfma_f32_16x16x32_bf16 v[16:19], v[160:163], v[218:221], v[16:19]
	v_mfma_f32_16x16x32_bf16 v[48:51], v[164:167], v[218:221], v[48:51]
	v_mfma_f32_16x16x32_bf16 v[80:83], v[168:171], v[218:221], v[80:83]
	v_mfma_f32_16x16x32_bf16 v[112:115], v[172:175], v[218:221], v[112:115]
	v_mfma_f32_16x16x32_bf16 v[20:23], v[160:163], v[222:225], v[20:23]
	v_mfma_f32_16x16x32_bf16 v[52:55], v[164:167], v[222:225], v[52:55]
	v_mfma_f32_16x16x32_bf16 v[84:87], v[168:171], v[222:225], v[84:87]
	v_mfma_f32_16x16x32_bf16 v[116:119], v[172:175], v[222:225], v[116:119]
	v_mfma_f32_16x16x32_bf16 v[24:27], v[160:163], v[226:229], v[24:27]
	v_mfma_f32_16x16x32_bf16 v[56:59], v[164:167], v[226:229], v[56:59]
	v_mfma_f32_16x16x32_bf16 v[88:91], v[168:171], v[226:229], v[88:91]
	v_mfma_f32_16x16x32_bf16 v[120:123], v[172:175], v[226:229], v[120:123]
	v_mfma_f32_16x16x32_bf16 v[28:31], v[160:163], v[230:233], v[28:31]
	v_mfma_f32_16x16x32_bf16 v[60:63], v[164:167], v[230:233], v[60:63]
	v_mfma_f32_16x16x32_bf16 v[92:95], v[168:171], v[230:233], v[92:95]
	v_mfma_f32_16x16x32_bf16 v[124:127], v[172:175], v[230:233], v[124:127]
	s_waitcnt vmcnt(16)
	global_load_dwordx4 v[160:163], v238, s[56:57]
	global_load_dwordx4 v[164:167], v239, s[56:57]
	global_load_dwordx4 v[168:171], v240, s[56:57]
	global_load_dwordx4 v[172:175], v241, s[56:57]
	s_cmp_eq_u32 s25, 31
	s_cbranch_scc1 .Lg1_sww5
	s_add_u32 s56, s56, 1024
	s_addc_u32 s57, s57, 0
	s_branch .Lg1_swdw5

.Lg1_ndw5:
.Lg1_swdw5:
	s_add_i32 s25, s25, 1
	ds_read_b128 v[198:201], v245 offset:0
	ds_read_b128 v[202:205], v245 offset:2048
	ds_read_b128 v[210:213], v245 offset:4096
	ds_read_b128 v[214:217], v245 offset:6144
	ds_read_b128 v[218:221], v245 offset:8192
	ds_read_b128 v[222:225], v245 offset:10240
	ds_read_b128 v[226:229], v245 offset:12288
	ds_read_b128 v[230:233], v245 offset:14336
	s_waitcnt lgkmcnt(4)
	v_mfma_f32_16x16x32_bf16 v[0:3], v[176:179], v[198:201], v[0:3]
	v_mfma_f32_16x16x32_bf16 v[32:35], v[182:185], v[198:201], v[32:35]
	v_mfma_f32_16x16x32_bf16 v[64:67], v[186:189], v[198:201], v[64:67]
	v_mfma_f32_16x16x32_bf16 v[96:99], v[194:197], v[198:201], v[96:99]
	v_mfma_f32_16x16x32_bf16 v[4:7], v[176:179], v[202:205], v[4:7]
	v_mfma_f32_16x16x32_bf16 v[36:39], v[182:185], v[202:205], v[36:39]
	v_mfma_f32_16x16x32_bf16 v[68:71], v[186:189], v[202:205], v[68:71]
	v_mfma_f32_16x16x32_bf16 v[100:103], v[194:197], v[202:205], v[100:103]
	v_mfma_f32_16x16x32_bf16 v[8:11], v[176:179], v[210:213], v[8:11]
	v_mfma_f32_16x16x32_bf16 v[40:43], v[182:185], v[210:213], v[40:43]
	v_mfma_f32_16x16x32_bf16 v[72:75], v[186:189], v[210:213], v[72:75]
	v_mfma_f32_16x16x32_bf16 v[104:107], v[194:197], v[210:213], v[104:107]
	v_mfma_f32_16x16x32_bf16 v[12:15], v[176:179], v[214:217], v[12:15]
	v_mfma_f32_16x16x32_bf16 v[44:47], v[182:185], v[214:217], v[44:47]
	v_mfma_f32_16x16x32_bf16 v[76:79], v[186:189], v[214:217], v[76:79]
	v_mfma_f32_16x16x32_bf16 v[108:111], v[194:197], v[214:217], v[108:111]
	s_waitcnt lgkmcnt(0)
	v_mfma_f32_16x16x32_bf16 v[16:19], v[176:179], v[218:221], v[16:19]
	v_mfma_f32_16x16x32_bf16 v[48:51], v[182:185], v[218:221], v[48:51]
	v_mfma_f32_16x16x32_bf16 v[80:83], v[186:189], v[218:221], v[80:83]
	v_mfma_f32_16x16x32_bf16 v[112:115], v[194:197], v[218:221], v[112:115]
	v_mfma_f32_16x16x32_bf16 v[20:23], v[176:179], v[222:225], v[20:23]
	v_mfma_f32_16x16x32_bf16 v[52:55], v[182:185], v[222:225], v[52:55]
	v_mfma_f32_16x16x32_bf16 v[84:87], v[186:189], v[222:225], v[84:87]
	v_mfma_f32_16x16x32_bf16 v[116:119], v[194:197], v[222:225], v[116:119]
	v_mfma_f32_16x16x32_bf16 v[24:27], v[176:179], v[226:229], v[24:27]
	v_mfma_f32_16x16x32_bf16 v[56:59], v[182:185], v[226:229], v[56:59]
	v_mfma_f32_16x16x32_bf16 v[88:91], v[186:189], v[226:229], v[88:91]
	v_mfma_f32_16x16x32_bf16 v[120:123], v[194:197], v[226:229], v[120:123]
	v_mfma_f32_16x16x32_bf16 v[28:31], v[176:179], v[230:233], v[28:31]
	v_mfma_f32_16x16x32_bf16 v[60:63], v[182:185], v[230:233], v[60:63]
	v_mfma_f32_16x16x32_bf16 v[92:95], v[186:189], v[230:233], v[92:95]
	v_mfma_f32_16x16x32_bf16 v[124:127], v[194:197], v[230:233], v[124:127]
	s_add_i32 s28, s28, 0x4000
	s_cmp_lt_u32 s28, 0xc000
	s_cselect_b32 s28, s28, 0
	s_add_i32 s27, s27, 0x4000
	s_cmp_lt_u32 s27, 0xc000
	s_cselect_b32 s27, s27, 0
	s_add_i32 s29, s29, 1
	s_cmp_lt_u32 s29, 16
	s_cbranch_scc1 .Lg1_loop
	s_mov_b32 s32, 0
	s_add_i32 s0, s30, s36
	s_cmp_lt_i32 s0, s31
	s_cbranch_scc0 .Lg1_nf
	s_cmp_eq_u64 s[2:3], 0
	s_cbranch_scc0 .Lg1_nf
	s_mov_b32 s32, 0x600d0000
	s_or_b32 s32, s32, s28
.Lg1_nf:
	s_nop 7
	s_nop 7
	v_and_b32_e32 v198, 63, v208
	v_lshrrev_b32_e32 v199, 6, v208
	v_and_b32_e32 v200, 15, v198
	v_lshrrev_b32_e32 v201, 4, v198
	s_mul_i32 s0, s24, 0xb0000
	s_lshl_b32 s25, s26, 9
	s_add_i32 s0, s0, s25
	s_add_i32 s0, s0, 0x8000000
	v_mul_u32_u24_e32 v244, 0x1600, v200
	v_lshl_add_u32 v244, v199, 7, v244
	v_lshl_add_u32 v244, v201, 3, v244
	v_add_u32_e32 v244, s0, v244
	v_mov_b32_e32 v245, s93
	v_add_co_u32_e32 v244, vcc, s92, v244
	s_nop 1
	v_addc_co_u32_e32 v245, vcc, 0, v245, vcc
	v_mul_f32_e32 v0, v246, v0
	v_mul_f32_e32 v1, v246, v1
	v_mul_f32_e32 v2, v246, v2
	v_mul_f32_e32 v3, v246, v3
	v_cvt_pk_bf16_f32 v202, v0, v1
	v_cvt_pk_bf16_f32 v203, v2, v3
	global_store_dwordx2 v[244:245], v[202:203], off offset:0
	v_mul_f32_e32 v32, v246, v32
	v_mul_f32_e32 v33, v246, v33
	v_mul_f32_e32 v34, v246, v34
	v_mul_f32_e32 v35, v246, v35
	v_cvt_pk_bf16_f32 v204, v32, v33
	v_cvt_pk_bf16_f32 v205, v34, v35
	global_store_dwordx2 v[244:245], v[204:205], off offset:32
	v_mul_f32_e32 v64, v246, v64
	v_mul_f32_e32 v65, v246, v65
	v_mul_f32_e32 v66, v246, v66
	v_mul_f32_e32 v67, v246, v67
	v_cvt_pk_bf16_f32 v210, v64, v65
	v_cvt_pk_bf16_f32 v211, v66, v67
	global_store_dwordx2 v[244:245], v[210:211], off offset:64
	v_mul_f32_e32 v96, v246, v96
	v_mul_f32_e32 v97, v246, v97
	v_mul_f32_e32 v98, v246, v98
	v_mul_f32_e32 v99, v246, v99
	v_cvt_pk_bf16_f32 v212, v96, v97
	v_cvt_pk_bf16_f32 v213, v98, v99
	global_store_dwordx2 v[244:245], v[212:213], off offset:96
	v_add_co_u32_e32 v244, vcc, 0x16000, v244
	s_nop 1
	v_addc_co_u32_e32 v245, vcc, 0, v245, vcc
	v_mul_f32_e32 v4, v247, v4
	v_mul_f32_e32 v5, v247, v5
	v_mul_f32_e32 v6, v247, v6
	v_mul_f32_e32 v7, v247, v7
	v_cvt_pk_bf16_f32 v202, v4, v5
	v_cvt_pk_bf16_f32 v203, v6, v7
	global_store_dwordx2 v[244:245], v[202:203], off offset:0
	v_mul_f32_e32 v36, v247, v36
	v_mul_f32_e32 v37, v247, v37
	v_mul_f32_e32 v38, v247, v38
	v_mul_f32_e32 v39, v247, v39
	v_cvt_pk_bf16_f32 v204, v36, v37
	v_cvt_pk_bf16_f32 v205, v38, v39
	global_store_dwordx2 v[244:245], v[204:205], off offset:32
	v_mul_f32_e32 v68, v247, v68
	v_mul_f32_e32 v69, v247, v69
	v_mul_f32_e32 v70, v247, v70
	v_mul_f32_e32 v71, v247, v71
	v_cvt_pk_bf16_f32 v210, v68, v69
	v_cvt_pk_bf16_f32 v211, v70, v71
	global_store_dwordx2 v[244:245], v[210:211], off offset:64
	v_mul_f32_e32 v100, v247, v100
	v_mul_f32_e32 v101, v247, v101
	v_mul_f32_e32 v102, v247, v102
	v_mul_f32_e32 v103, v247, v103
	v_cvt_pk_bf16_f32 v212, v100, v101
	v_cvt_pk_bf16_f32 v213, v102, v103
	global_store_dwordx2 v[244:245], v[212:213], off offset:96
	v_add_co_u32_e32 v244, vcc, 0x16000, v244
	s_nop 1
	v_addc_co_u32_e32 v245, vcc, 0, v245, vcc
	v_mul_f32_e32 v8, v248, v8
	v_mul_f32_e32 v9, v248, v9
	v_mul_f32_e32 v10, v248, v10
	v_mul_f32_e32 v11, v248, v11
	v_cvt_pk_bf16_f32 v202, v8, v9
	v_cvt_pk_bf16_f32 v203, v10, v11
	global_store_dwordx2 v[244:245], v[202:203], off offset:0
	v_mul_f32_e32 v40, v248, v40
	v_mul_f32_e32 v41, v248, v41
	v_mul_f32_e32 v42, v248, v42
	v_mul_f32_e32 v43, v248, v43
	v_cvt_pk_bf16_f32 v204, v40, v41
	v_cvt_pk_bf16_f32 v205, v42, v43
	global_store_dwordx2 v[244:245], v[204:205], off offset:32
	v_mul_f32_e32 v72, v248, v72
	v_mul_f32_e32 v73, v248, v73
	v_mul_f32_e32 v74, v248, v74
	v_mul_f32_e32 v75, v248, v75
	v_cvt_pk_bf16_f32 v210, v72, v73
	v_cvt_pk_bf16_f32 v211, v74, v75
	global_store_dwordx2 v[244:245], v[210:211], off offset:64
	v_mul_f32_e32 v104, v248, v104
	v_mul_f32_e32 v105, v248, v105
	v_mul_f32_e32 v106, v248, v106
	v_mul_f32_e32 v107, v248, v107
	v_cvt_pk_bf16_f32 v212, v104, v105
	v_cvt_pk_bf16_f32 v213, v106, v107
	global_store_dwordx2 v[244:245], v[212:213], off offset:96
	v_add_co_u32_e32 v244, vcc, 0x16000, v244
	s_nop 1
	v_addc_co_u32_e32 v245, vcc, 0, v245, vcc
	v_mul_f32_e32 v12, v249, v12
	v_mul_f32_e32 v13, v249, v13
	v_mul_f32_e32 v14, v249, v14
	v_mul_f32_e32 v15, v249, v15
	v_cvt_pk_bf16_f32 v202, v12, v13
	v_cvt_pk_bf16_f32 v203, v14, v15
	global_store_dwordx2 v[244:245], v[202:203], off offset:0
	v_mul_f32_e32 v44, v249, v44
	v_mul_f32_e32 v45, v249, v45
	v_mul_f32_e32 v46, v249, v46
	v_mul_f32_e32 v47, v249, v47
	v_cvt_pk_bf16_f32 v204, v44, v45
	v_cvt_pk_bf16_f32 v205, v46, v47
	global_store_dwordx2 v[244:245], v[204:205], off offset:32
	v_mul_f32_e32 v76, v249, v76
	v_mul_f32_e32 v77, v249, v77
	v_mul_f32_e32 v78, v249, v78
	v_mul_f32_e32 v79, v249, v79
	v_cvt_pk_bf16_f32 v210, v76, v77
	v_cvt_pk_bf16_f32 v211, v78, v79
	global_store_dwordx2 v[244:245], v[210:211], off offset:64
	v_mul_f32_e32 v108, v249, v108
	v_mul_f32_e32 v109, v249, v109
	v_mul_f32_e32 v110, v249, v110
	v_mul_f32_e32 v111, v249, v111
	v_cvt_pk_bf16_f32 v212, v108, v109
	v_cvt_pk_bf16_f32 v213, v110, v111
	global_store_dwordx2 v[244:245], v[212:213], off offset:96
	v_add_co_u32_e32 v244, vcc, 0x16000, v244
	s_nop 1
	v_addc_co_u32_e32 v245, vcc, 0, v245, vcc
	v_mul_f32_e32 v16, v250, v16
	v_mul_f32_e32 v17, v250, v17
	v_mul_f32_e32 v18, v250, v18
	v_mul_f32_e32 v19, v250, v19
	v_cvt_pk_bf16_f32 v202, v16, v17
	v_cvt_pk_bf16_f32 v203, v18, v19
	global_store_dwordx2 v[244:245], v[202:203], off offset:0
	v_mul_f32_e32 v48, v250, v48
	v_mul_f32_e32 v49, v250, v49
	v_mul_f32_e32 v50, v250, v50
	v_mul_f32_e32 v51, v250, v51
	v_cvt_pk_bf16_f32 v204, v48, v49
	v_cvt_pk_bf16_f32 v205, v50, v51
	global_store_dwordx2 v[244:245], v[204:205], off offset:32
	v_mul_f32_e32 v80, v250, v80
	v_mul_f32_e32 v81, v250, v81
	v_mul_f32_e32 v82, v250, v82
	v_mul_f32_e32 v83, v250, v83
	v_cvt_pk_bf16_f32 v210, v80, v81
	v_cvt_pk_bf16_f32 v211, v82, v83
	global_store_dwordx2 v[244:245], v[210:211], off offset:64
	v_mul_f32_e32 v112, v250, v112
	v_mul_f32_e32 v113, v250, v113
	v_mul_f32_e32 v114, v250, v114
	v_mul_f32_e32 v115, v250, v115
	v_cvt_pk_bf16_f32 v212, v112, v113
	v_cvt_pk_bf16_f32 v213, v114, v115
	global_store_dwordx2 v[244:245], v[212:213], off offset:96
	v_add_co_u32_e32 v244, vcc, 0x16000, v244
	s_nop 1
	v_addc_co_u32_e32 v245, vcc, 0, v245, vcc
	v_mul_f32_e32 v20, v251, v20
	v_mul_f32_e32 v21, v251, v21
	v_mul_f32_e32 v22, v251, v22
	v_mul_f32_e32 v23, v251, v23
	v_cvt_pk_bf16_f32 v202, v20, v21
	v_cvt_pk_bf16_f32 v203, v22, v23
	global_store_dwordx2 v[244:245], v[202:203], off offset:0
	v_mul_f32_e32 v52, v251, v52
	v_mul_f32_e32 v53, v251, v53
	v_mul_f32_e32 v54, v251, v54
	v_mul_f32_e32 v55, v251, v55
	v_cvt_pk_bf16_f32 v204, v52, v53
	v_cvt_pk_bf16_f32 v205, v54, v55
	global_store_dwordx2 v[244:245], v[204:205], off offset:32
	v_mul_f32_e32 v84, v251, v84
	v_mul_f32_e32 v85, v251, v85
	v_mul_f32_e32 v86, v251, v86
	v_mul_f32_e32 v87, v251, v87
	v_cvt_pk_bf16_f32 v210, v84, v85
	v_cvt_pk_bf16_f32 v211, v86, v87
	global_store_dwordx2 v[244:245], v[210:211], off offset:64
	v_mul_f32_e32 v116, v251, v116
	v_mul_f32_e32 v117, v251, v117
	v_mul_f32_e32 v118, v251, v118
	v_mul_f32_e32 v119, v251, v119
	v_cvt_pk_bf16_f32 v212, v116, v117
	v_cvt_pk_bf16_f32 v213, v118, v119
	global_store_dwordx2 v[244:245], v[212:213], off offset:96
	v_add_co_u32_e32 v244, vcc, 0x16000, v244
	s_nop 1
	v_addc_co_u32_e32 v245, vcc, 0, v245, vcc
	v_mul_f32_e32 v24, v252, v24
	v_mul_f32_e32 v25, v252, v25
	v_mul_f32_e32 v26, v252, v26
	v_mul_f32_e32 v27, v252, v27
	v_cvt_pk_bf16_f32 v202, v24, v25
	v_cvt_pk_bf16_f32 v203, v26, v27
	global_store_dwordx2 v[244:245], v[202:203], off offset:0
	v_mul_f32_e32 v56, v252, v56
	v_mul_f32_e32 v57, v252, v57
	v_mul_f32_e32 v58, v252, v58
	v_mul_f32_e32 v59, v252, v59
	v_cvt_pk_bf16_f32 v204, v56, v57
	v_cvt_pk_bf16_f32 v205, v58, v59
	global_store_dwordx2 v[244:245], v[204:205], off offset:32
	v_mul_f32_e32 v88, v252, v88
	v_mul_f32_e32 v89, v252, v89
	v_mul_f32_e32 v90, v252, v90
	v_mul_f32_e32 v91, v252, v91
	v_cvt_pk_bf16_f32 v210, v88, v89
	v_cvt_pk_bf16_f32 v211, v90, v91
	global_store_dwordx2 v[244:245], v[210:211], off offset:64
	v_mul_f32_e32 v120, v252, v120
	v_mul_f32_e32 v121, v252, v121
	v_mul_f32_e32 v122, v252, v122
	v_mul_f32_e32 v123, v252, v123
	v_cvt_pk_bf16_f32 v212, v120, v121
	v_cvt_pk_bf16_f32 v213, v122, v123
	global_store_dwordx2 v[244:245], v[212:213], off offset:96
	v_add_co_u32_e32 v244, vcc, 0x16000, v244
	s_nop 1
	v_addc_co_u32_e32 v245, vcc, 0, v245, vcc
	v_mul_f32_e32 v28, v253, v28
	v_mul_f32_e32 v29, v253, v29
	v_mul_f32_e32 v30, v253, v30
	v_mul_f32_e32 v31, v253, v31
	v_cvt_pk_bf16_f32 v202, v28, v29
	v_cvt_pk_bf16_f32 v203, v30, v31
	global_store_dwordx2 v[244:245], v[202:203], off offset:0
	v_mul_f32_e32 v60, v253, v60
	v_mul_f32_e32 v61, v253, v61
	v_mul_f32_e32 v62, v253, v62
	v_mul_f32_e32 v63, v253, v63
	v_cvt_pk_bf16_f32 v204, v60, v61
	v_cvt_pk_bf16_f32 v205, v62, v63
	global_store_dwordx2 v[244:245], v[204:205], off offset:32
	v_mul_f32_e32 v92, v253, v92
	v_mul_f32_e32 v93, v253, v93
	v_mul_f32_e32 v94, v253, v94
	v_mul_f32_e32 v95, v253, v95
	v_cvt_pk_bf16_f32 v210, v92, v93
	v_cvt_pk_bf16_f32 v211, v94, v95
	global_store_dwordx2 v[244:245], v[210:211], off offset:64
	v_mul_f32_e32 v124, v253, v124
	v_mul_f32_e32 v125, v253, v125
	v_mul_f32_e32 v126, v253, v126
	v_mul_f32_e32 v127, v253, v127
	v_cvt_pk_bf16_f32 v212, v124, v125
	v_cvt_pk_bf16_f32 v213, v126, v127
	global_store_dwordx2 v[244:245], v[212:213], off offset:96

	s_add_i32 s30, s30, s36
	s_cmp_lt_i32 s30, s31
	s_cbranch_scc1 .LBB0_154
